# attention MID key tiles (all distances in (128,512]): 8-score fast path (select the (q-key)%4==0 scores, same fma bias, 8-wide softmax, scatter into the P fragments) instead of the 32-score general pa
# speedup vs baseline: 1.0018x; 1.0018x over previous
; #define LAS __attribute__((address_space(3)))
; __device__ __forceinline__ unsigned xb_add(unsigned* p, unsigned v) { return __hip_atomic_fetch_add(p, v, __ATOMIC_RELAXED, __HIP_MEMORY_SCOPE_AGENT); }
; __device__ __forceinline__ unsigned xb_xcc_id() { return (unsigned)__builtin_amdgcn_s_getreg((3 << 11) | 20) & 0xFu; }
; __device__ __forceinline__ XcdBarrier xcd_barrier_post(unsigned* bar, volatile LAS unsigned* st) {
;     XcdBarrier b; b.bar = bar; b.x = xb_xcc_id(); b.st = st;
;     if (threadIdx.x == 0) (void)xb_add(&bar[XB_XCNT(b.x)], 1u);
;     return b;
; }
.LBB0_7:
	s_or_b64 exec, exec, s[6:7]
	s_cmp_eq_u32 s99, 1
	s_mov_b32 s99, 0
	s_cbranch_scc0 .Lgb_post_ok
	s_mov_b64 exec, s[96:97]
	s_cbranch_execz .Lgb_post_skip
	v_mov_b32_e32 v254, 0x2d000
	v_mov_b32_e32 v255, 1
	global_atomic_add v254, v255, s[76:77]
	s_branch .Lgb_post_skip
.Lgb_post_ok:
.Lgb_post_skip:
	s_mov_b64 exec, -1

; template <int CLS> __device__ __forceinline__ void bias_tile(f32x16& p0, f32x16& p1, int dq, float slr, int dq15, int dq3) {
;     ...
;             else if (CLS == 1) { const float v2 = v + L2R; v = m16 ? v2 : v; v = m4 ? v : NEG; }
; __device__ __forceinline__ void attn_block(const bf16_t* __restrict__ proj, bf16_t* __restrict__ mixed, int b, int h, int qb, char* lds) {
;     ...
;                 const float NEG = -__builtin_inff();
;                 float e0 = FA_SEL8(p0, 0) + fc0, e1 = FA_SEL8(p0, 8) + (fc0 + 16.f * slr), e2 = FA_SEL8(p1, 0) + (fc0 + 32.f * slr), e3 = FA_SEL8(p1, 8) + (fc0 + 48.f * slr);
;     ...
;                 e0 = lane_valid ? e0 : NEG; e1 = lane_valid ? e1 : NEG; e2 = lane_valid ? e2 : NEG; e3 = lane_valid ? e3 : NEG;
;                 float pmax = fmaxf(fmaxf(e0, e1), fmaxf(e2, e3));
;                 { auto rr = __builtin_amdgcn_permlane32_swap(__float_as_uint(pmax), __float_as_uint(pmax), false, false); pmax = fmaxf(__uint_as_float(rr[0]), __uint_as_float(rr[1])); }
;                 constexpr float C2 = LOG2E * SCALE; float mn;
;                 if (__builtin_expect(__all((pmax - m_reg) * SCALE <= THR), 1)) { mn = m_reg; alpha = 1.f; }
;                 else { mn = fmaxf(m_reg, pmax); alpha = __builtin_amdgcn_exp2f((m_reg - mn) * C2); m_reg = mn; }
;                 const float mnL = -mn * C2;
;                 e0 = __builtin_amdgcn_exp2f(__builtin_fmaf(e0, C2, mnL)); e1 = __builtin_amdgcn_exp2f(__builtin_fmaf(e1, C2, mnL));
;                 e2 = __builtin_amdgcn_exp2f(__builtin_fmaf(e2, C2, mnL)); e3 = __builtin_amdgcn_exp2f(__builtin_fmaf(e3, C2, mnL));
;                 float ps = (e0 + e1) + (e2 + e3);
;                 { auto rr = __builtin_amdgcn_permlane32_swap(__float_as_uint(ps), __float_as_uint(ps), false, false); ps = __uint_as_float(rr[0]) + __uint_as_float(rr[1]); }
;                 l_reg = l_reg * alpha + ps;
;     ...
;                 FA_SCAT(e0, pa0); FA_SCAT(e1, pa1); FA_SCAT(e2, pa2); FA_SCAT(e3, pa3);
.Lmid_fast:
	s_nop 3
	v_and_b32_e32 v132, 3, v0
	v_and_b32_e32 v134, 12, v0
	v_cvt_f32_u32_e32 v133, v132
	v_cmp_eq_u32_e32 vcc, 1, v132
	v_cndmask_b32_e32 v116, v96, v97, vcc
	v_cndmask_b32_e32 v117, v100, v101, vcc
	v_cndmask_b32_e32 v118, v104, v105, vcc
	v_cndmask_b32_e32 v119, v108, v109, vcc
	v_cndmask_b32_e32 v120, v80, v81, vcc
	v_cndmask_b32_e32 v121, v84, v85, vcc
	v_cndmask_b32_e32 v122, v88, v89, vcc
	v_cndmask_b32_e32 v123, v92, v93, vcc
	v_cmp_eq_u32_e32 vcc, 2, v132
	v_cndmask_b32_e32 v116, v116, v98, vcc
	v_cndmask_b32_e32 v117, v117, v102, vcc
	v_cndmask_b32_e32 v118, v118, v106, vcc
	v_cndmask_b32_e32 v119, v119, v110, vcc
	v_cndmask_b32_e32 v120, v120, v82, vcc
	v_cndmask_b32_e32 v121, v121, v86, vcc
	v_cndmask_b32_e32 v122, v122, v90, vcc
	v_cndmask_b32_e32 v123, v123, v94, vcc
	v_cmp_eq_u32_e32 vcc, 3, v132
	v_cndmask_b32_e32 v116, v116, v99, vcc
	v_cndmask_b32_e32 v117, v117, v103, vcc
	v_cndmask_b32_e32 v118, v118, v107, vcc
	v_cndmask_b32_e32 v119, v119, v111, vcc
	v_cndmask_b32_e32 v120, v120, v83, vcc
	v_cndmask_b32_e32 v121, v121, v87, vcc
	v_cndmask_b32_e32 v122, v122, v91, vcc
	v_cndmask_b32_e32 v123, v123, v95, vcc
	v_add_f32_e32 v125, 0x41000000, v133
	v_add_f32_e32 v126, 0x41800000, v133
	v_add_f32_e32 v127, 0x41c00000, v133
	v_add_f32_e32 v128, 0x42000000, v133
	v_add_f32_e32 v129, 0x42200000, v133
	v_add_f32_e32 v130, 0x42400000, v133
	v_add_f32_e32 v131, 0x42600000, v133
	v_fma_f32 v116, v203, v133, v116
	v_fma_f32 v117, v203, v125, v117
	v_fma_f32 v118, v203, v126, v118
	v_fma_f32 v119, v203, v127, v119
	v_fma_f32 v120, v203, v128, v120
	v_fma_f32 v121, v203, v129, v121
	v_fma_f32 v122, v203, v130, v122
	v_fma_f32 v123, v203, v131, v123
	v_cmp_eq_u32_e32 vcc, 0, v134
	v_add_f32_e32 v138, 0x40faf233, v116
	v_cndmask_b32_e32 v116, v116, v138, vcc
	v_add_f32_e32 v138, 0x40faf233, v118
	v_cndmask_b32_e32 v118, v118, v138, vcc
	v_add_f32_e32 v138, 0x40faf233, v120
	v_cndmask_b32_e32 v120, v120, v138, vcc
	v_add_f32_e32 v138, 0x40faf233, v122
	v_cndmask_b32_e32 v122, v122, v138, vcc
	v_cmp_eq_u32_e32 vcc, 8, v134
	v_add_f32_e32 v138, 0x40faf233, v117
	v_cndmask_b32_e32 v117, v117, v138, vcc
	v_add_f32_e32 v138, 0x40faf233, v119
	v_cndmask_b32_e32 v119, v119, v138, vcc
	v_add_f32_e32 v138, 0x40faf233, v121
	v_cndmask_b32_e32 v121, v121, v138, vcc
	v_add_f32_e32 v138, 0x40faf233, v123
	v_cndmask_b32_e32 v123, v123, v138, vcc
	v_max3_f32 v0, v116, v117, v118
	v_max3_f32 v0, v0, v119, v120
	v_max3_f32 v0, v0, v121, v122
	v_max_f32_e32 v0, v0, v123
	v_mov_b32_e32 v2, v0
	s_nop 1
	v_permlane32_swap_b32_e32 v0, v2
	v_max_f32_e32 v2, v2, v2
	v_max_f32_e32 v0, v0, v0
	v_max_f32_e32 v0, v0, v2
	v_sub_f32_e32 v2, v0, v234
	v_mul_f32_e32 v2, 0x3db504f3, v2
	v_cmp_ge_f32_e32 vcc, s58, v2
	v_max_f32_e32 v2, v234, v234
	v_max_f32_e32 v0, v2, v0
	v_sub_f32_e32 v2, v234, v0
	v_mul_f32_e32 v2, 0x3e0293ee, v2
	v_exp_f32_e32 v2, v2
	s_cmp_eq_u64 vcc, exec
	s_cselect_b64 vcc, -1, 0
	v_cndmask_b32_e32 v14, v0, v234, vcc
	v_mul_f32_e32 v0, 0xbe0293ee, v14
	v_cndmask_b32_e64 v235, v2, 1.0, vcc
	v_fmamk_f32 v116, v116, 0x3e0293ee, v0
	v_fmamk_f32 v117, v117, 0x3e0293ee, v0
	v_fmamk_f32 v118, v118, 0x3e0293ee, v0
	v_fmamk_f32 v119, v119, 0x3e0293ee, v0
	v_fmamk_f32 v120, v120, 0x3e0293ee, v0
	v_fmamk_f32 v121, v121, 0x3e0293ee, v0
	v_fmamk_f32 v122, v122, 0x3e0293ee, v0
	v_fmamk_f32 v123, v123, 0x3e0293ee, v0
	v_exp_f32_e32 v116, v116
	v_exp_f32_e32 v117, v117
	v_exp_f32_e32 v118, v118
	v_exp_f32_e32 v119, v119
	v_exp_f32_e32 v120, v120
	v_exp_f32_e32 v121, v121
	v_exp_f32_e32 v122, v122
	v_exp_f32_e32 v123, v123
	v_and_b32_e32 v135, 1, v132
	v_lshlrev_b32_e32 v135, 4, v135
	v_add_f32_e32 v15, v116, v117
	v_add_f32_e32 v15, v118, v15
	v_add_f32_e32 v15, v119, v15
	v_add_f32_e32 v15, v120, v15
	v_add_f32_e32 v15, v121, v15
	v_add_f32_e32 v15, v122, v15
	v_add_f32_e32 v15, v123, v15
	v_mov_b32_e32 v0, v15
	s_nop 1
	v_permlane32_swap_b32_e32 v15, v0
	v_add_f32_e32 v15, v15, v0
	v_fmac_f32_e32 v15, v233, v235
	v_cmp_gt_u32_e32 vcc, 2, v132
	v_cvt_pk_bf16_f32 v136, v116, 0
	v_cvt_pk_bf16_f32 v137, v117, 0
	v_lshlrev_b32_e32 v136, v135, v136
	v_lshlrev_b32_e32 v137, v135, v137
	v_cndmask_b32_e32 v2, 0, v136, vcc
	v_cndmask_b32_e64 v3, v136, 0, vcc
	v_cndmask_b32_e32 v4, 0, v137, vcc
	v_cndmask_b32_e64 v5, v137, 0, vcc
	v_cvt_pk_bf16_f32 v136, v118, 0
	v_cvt_pk_bf16_f32 v137, v119, 0
	v_lshlrev_b32_e32 v136, v135, v136
	v_lshlrev_b32_e32 v137, v135, v137
	v_cndmask_b32_e32 v6, 0, v136, vcc
	v_cndmask_b32_e64 v7, v136, 0, vcc
	v_cndmask_b32_e32 v8, 0, v137, vcc
	v_cndmask_b32_e64 v9, v137, 0, vcc
	v_cvt_pk_bf16_f32 v136, v120, 0
	v_cvt_pk_bf16_f32 v137, v121, 0
	v_lshlrev_b32_e32 v136, v135, v136
	v_lshlrev_b32_e32 v137, v135, v137
	v_cndmask_b32_e32 v10, 0, v136, vcc
	v_cndmask_b32_e64 v11, v136, 0, vcc
	v_cndmask_b32_e32 v12, 0, v137, vcc
	v_cndmask_b32_e64 v13, v137, 0, vcc
	v_cvt_pk_bf16_f32 v136, v122, 0
	v_cvt_pk_bf16_f32 v137, v123, 0
	v_lshlrev_b32_e32 v136, v135, v136
	v_lshlrev_b32_e32 v137, v135, v137
	v_cndmask_b32_e32 v112, 0, v136, vcc
	v_cndmask_b32_e64 v113, v136, 0, vcc
	v_cndmask_b32_e32 v114, 0, v137, vcc
	v_cndmask_b32_e64 v115, v137, 0, vcc
	s_nop 1
	v_permlane32_swap_b32_e32 v2, v4
	v_permlane32_swap_b32_e32 v3, v5
	v_permlane32_swap_b32_e32 v6, v8
	v_permlane32_swap_b32_e32 v7, v9
	v_permlane32_swap_b32_e32 v10, v12
	v_permlane32_swap_b32_e32 v11, v13
	v_permlane32_swap_b32_e32 v112, v114
	v_permlane32_swap_b32_e32 v113, v115
	s_branch .LBB0_315
